# attention tile loop: common path straightened (loop-edge edits: barriers inlined, rare blocks out of line, back-edge header duplicated before the barrier, resc test hoisted)
# speedup vs baseline: 1.0185x; 1.0067x over previous
; #define PBAR_M(t) do { if ((t) + 3 < NT) { WAIT_BAR(6); } else { WAIT_BAR(0); } } while (0)
; template <int VAR> __device__ __forceinline__ void block(const bf16* Q, const bf16* KVB, const bf16* KR, const float* cosT, bf16* OB, LAS unsigned char* lds, int b, int h, int qb, int t0, int wv, ...
;     ...
; #pragma unroll 1
;     for (int t = 1; t < NT; ++t) {
;         PBAR_M(t);
.LBB0_1408:
	s_cmp_ge_u32 s85, s66
	s_cselect_b64 s[4:5], -1, 0
	s_cbranch_scc1 .Lat_mbar0
	s_waitcnt vmcnt(6) lgkmcnt(0)
	s_barrier

; #define SBAR() __builtin_amdgcn_sched_barrier(0)
; #define MASKT(P0_, P1_, t) do { const int kbm_ = TT(t) * 64; if (kbm_ + 63 > qlo) mask_tile(P0_, P1_, qm - kbm_); } while (0)
; #define PBAR_V(t) do { if ((t) + 3 < NT) { WAIT_BAR(6); } else { WAIT_BAR(0); } } while (0)
; template <int VAR> __device__ __forceinline__ void block(const bf16* Q, const bf16* KVB, const bf16* KR, const float* cosT, bf16* OB, LAS unsigned char* lds, int b, int h, int qb, int t0, int wv, ...
;     ...
;         QK(px0, px1);
;         SBAR(); asm volatile("s_waitcnt lgkmcnt(0)" ::: "memory"); SBAR();
;         PVALL();
;         PBAR_V(t);
;         MASKT(px0, px1, t);
.Lat_nodmav:
	ds_read_b64_tr_b16 v[238:239], v255 offset:0x1000
	s_waitcnt lgkmcnt(14)
	v_mfma_f32_32x32x16_bf16 v[64:79], v[190:193], v[108:111], v[64:79]
	ds_read_b64_tr_b16 v[240:241], v255 offset:0x1200
	s_waitcnt lgkmcnt(14)
	v_mfma_f32_32x32x16_bf16 v[48:63], v[198:201], v[108:111], v[48:63]
	ds_read_b64_tr_b16 v[242:243], v255 offset:0x1400
	s_waitcnt lgkmcnt(14)
	v_mfma_f32_32x32x16_bf16 v[64:79], v[202:205], v[120:123], v[64:79]
	ds_read_b64_tr_b16 v[244:245], v255 offset:0x1600
	s_waitcnt lgkmcnt(14)
	v_mfma_f32_32x32x16_bf16 v[48:63], v[210:213], v[120:123], v[48:63]
	ds_read_b64_tr_b16 v[246:247], v255 offset:0x1800
	s_waitcnt lgkmcnt(14)
	v_mfma_f32_32x32x16_bf16 v[64:79], v[206:209], v[124:127], v[64:79]
	ds_read_b64_tr_b16 v[248:249], v255 offset:0x1a00
	s_waitcnt lgkmcnt(14)
	v_mfma_f32_32x32x16_bf16 v[48:63], v[214:217], v[124:127], v[48:63]
	ds_read_b64_tr_b16 v[250:251], v255 offset:0x1c00
	ds_read_b64_tr_b16 v[252:253], v255 offset:0x1e00
	s_waitcnt lgkmcnt(14)
	v_mfma_f32_32x32x16_bf16 v[16:31], v[140:143], v[220:223], v[16:31]
	s_and_b64 vcc, exec, s[4:5]
	s_waitcnt lgkmcnt(12)
	v_mfma_f32_32x32x16_bf16 v[16:31], v[136:139], v[226:229], v[16:31]
	s_waitcnt lgkmcnt(10)
	v_mfma_f32_32x32x16_bf16 v[16:31], v[132:135], v[230:233], v[16:31]
	s_waitcnt lgkmcnt(8)
	v_mfma_f32_32x32x16_bf16 v[16:31], v[128:131], v[234:237], v[16:31]
	s_waitcnt lgkmcnt(6)
	v_mfma_f32_32x32x16_bf16 v[0:15], v[140:143], v[238:241], v[0:15]
	s_waitcnt lgkmcnt(4)
	v_mfma_f32_32x32x16_bf16 v[0:15], v[136:139], v[242:245], v[0:15]
	s_waitcnt lgkmcnt(2)
	v_mfma_f32_32x32x16_bf16 v[0:15], v[132:135], v[246:249], v[0:15]
	s_waitcnt lgkmcnt(0)
	v_mfma_f32_32x32x16_bf16 v[0:15], v[128:131], v[250:253], v[0:15]
	s_setprio 0
	s_cbranch_vccnz .LBB0_1427
	s_waitcnt vmcnt(6) lgkmcnt(0)
	s_barrier
.LBB0_1415:
	s_cmp_le_u32 s33, s77
	s_cbranch_scc0 .LBB0_1416

; #define RESC(al) do { if (__any((al) < 1.f)) { if (hi == 0) al_l[r32] = (al); asm volatile("s_waitcnt lgkmcnt(0)" ::: "memory"); \
;         _Pragma("unroll") for (int d_ = 0; d_ < 2; ++d_) _Pragma("unroll") for (int r = 0; r < 16; ++r) o[d_][r] *= al_l[crow(r, hi)]; } } while (0)
; #define SHIFT(P0_, P1_, dl_) do { m_reg += (dl_); _Pragma("unroll") for (int r = 0; r < 16; ++r) { P0_[r] -= (dl_); P1_[r] -= (dl_); } _Pragma("unroll") for (int r = 0; r < 16; ++r) negm[r] = -m_reg; } while (0)
; template <int VAR> __device__ __forceinline__ void block(const bf16* Q, const bf16* KVB, const bf16* KR, const float* cosT, bf16* OB, LAS unsigned char* lds, int b, int h, int qb, int t0, int wv, ...
;     ...
;         float pm_, alX = 1.f; ROWMAX(px0, px1, pm_);
;         if (__builtin_expect(__any(pm_ > THR), 0)) { const float dl_ = fmaxf(pm_, 0.f); SHIFT(px0, px1, dl_); alX = __builtin_amdgcn_exp2f(-dl_); }
;         TILE_VALU(alX);
;         pa0 = pn0; pa1 = pn1; pa2 = pn2; pa3 = pn3;
;         RESC(alX);
;         sk = (sk + 1) & 3; sv = (sv + 1) & 3;
;     }
.LBB0_1418:
	v_cmp_gt_f32_e32 vcc, 1.0, v128
	v_exp_f32_e32 v64, v64
	v_exp_f32_e32 v68, v68
	v_exp_f32_e32 v129, v48
	v_exp_f32_e32 v52, v52
	v_exp_f32_e32 v65, v65
	v_exp_f32_e32 v69, v69
	v_exp_f32_e32 v49, v49
	v_exp_f32_e32 v53, v53
	v_exp_f32_e32 v66, v66
	v_exp_f32_e32 v70, v70
	v_exp_f32_e32 v50, v50
	v_exp_f32_e32 v54, v54
	v_exp_f32_e32 v67, v67
	v_exp_f32_e32 v71, v71
	v_exp_f32_e32 v51, v51
	v_exp_f32_e32 v55, v55
	v_exp_f32_e32 v72, v72
	v_exp_f32_e32 v56, v56
	v_add_f32_e32 v48, v129, v64
	v_add_f32_e32 v133, v52, v68
	v_exp_f32_e32 v73, v73
	v_exp_f32_e32 v57, v57
	v_add_f32_e32 v130, v49, v65
	v_add_f32_e32 v48, v48, v133
	v_add_f32_e32 v133, v53, v69
	v_exp_f32_e32 v74, v74
	v_exp_f32_e32 v58, v58
	v_add_f32_e32 v131, v50, v66
	v_add_f32_e32 v130, v130, v133
	v_add_f32_e32 v133, v54, v70
	v_exp_f32_e32 v75, v75
	v_exp_f32_e32 v59, v59
	v_add_f32_e32 v132, v51, v67
	v_add_f32_e32 v131, v131, v133
	v_add_f32_e32 v133, v55, v71
	v_exp_f32_e32 v76, v76
	v_exp_f32_e32 v60, v60
	v_add_f32_e32 v132, v132, v133
	v_add_f32_e32 v133, v56, v72
	v_exp_f32_e32 v77, v77
	v_exp_f32_e32 v61, v61
	v_add_f32_e32 v48, v133, v48
	v_add_f32_e32 v133, v57, v73
	v_exp_f32_e32 v78, v78
	v_exp_f32_e32 v62, v62
	v_add_f32_e32 v130, v133, v130
	v_add_f32_e32 v133, v58, v74
	v_exp_f32_e32 v79, v79
	v_exp_f32_e32 v63, v63
	v_add_f32_e32 v131, v133, v131
	v_add_f32_e32 v133, v59, v75
	v_add_f32_e32 v132, v133, v132
	v_add_f32_e32 v133, v60, v76
	v_add_f32_e32 v48, v133, v48
	v_add_f32_e32 v133, v61, v77
	v_add_f32_e32 v130, v133, v130
	v_add_f32_e32 v133, v62, v78
	v_add_f32_e32 v131, v133, v131
	v_add_f32_e32 v133, v63, v79
	v_add_f32_e32 v132, v133, v132
	v_add_f32_e32 v48, v48, v130
	v_add_f32_e32 v130, v131, v132
	v_add_f32_e32 v48, v48, v130
	v_mov_b32_e32 v130, v48
	s_nop 1
	v_permlane32_swap_b32_e32 v48, v130
	s_cbranch_vccnz .Lat_resc
.LBB0_1422:
	s_add_i32 s4, s82, 1
	s_and_b32 s82, s4, 3
	s_add_i32 s4, s68, 1
	s_add_i32 s85, s85, 1
	v_add_f32_e32 v48, v48, v130
	s_and_b32 s68, s4, 3
	s_add_i32 s4, s67, s85
	s_add_i32 s33, s33, 64
	v_fmac_f32_e32 v48, v150, v128
	v_cvt_pk_bf16_f32 v140, v64, v65
	v_cvt_pk_bf16_f32 v141, v66, v67
	v_cvt_pk_bf16_f32 v142, v68, v69
	v_cvt_pk_bf16_f32 v143, v70, v71
	v_cvt_pk_bf16_f32 v136, v72, v73
	v_cvt_pk_bf16_f32 v137, v74, v75
	v_cvt_pk_bf16_f32 v138, v76, v77
	v_cvt_pk_bf16_f32 v139, v78, v79
	v_cvt_pk_bf16_f32 v132, v129, v49
	v_cvt_pk_bf16_f32 v133, v50, v51
	v_cvt_pk_bf16_f32 v134, v52, v53
	v_cvt_pk_bf16_f32 v135, v54, v55
	v_cvt_pk_bf16_f32 v128, v56, v57
	v_cvt_pk_bf16_f32 v129, v58, v59
	v_cvt_pk_bf16_f32 v130, v60, v61
	v_cvt_pk_bf16_f32 v131, v62, v63
	v_subrev_u32_e32 v173, 64, v173
	v_lshl_add_u64 v[154:155], v[154:155], 0, s[94:95]
	v_lshl_add_u64 v[156:157], v[156:157], 0, s[70:71]
	s_cmp_eq_u32 s4, 4
	v_lshl_add_u64 v[158:159], v[158:159], 0, s[94:95]
	s_cbranch_scc1 .LBB0_1430
	v_mov_b32_e32 v150, v48
	s_cmp_ge_u32 s85, s66
	s_cselect_b64 s[4:5], -1, 0
	s_cbranch_scc1 .Lat_mbar0
	s_waitcnt vmcnt(6) lgkmcnt(0)
	s_barrier
	s_branch .Lat_mreads
.Lat_mbar0:
	s_waitcnt vmcnt(0) lgkmcnt(0)
	s_barrier
	s_branch .Lat_mreads
; __device__ __forceinline__ void mask_tile(f32x16& p0, f32x16& p1, int dq) {
;     const float NEG = -__builtin_inff();
; #pragma unroll
;     for (int r = 0; r < 16; ++r) { const int c = (r & 3) + 8 * (r >> 2); if (dq - c < 0) p0[r] = NEG; if (dq - c - 32 < 0) p1[r] = NEG; }
; }
.LBB0_1416:
	v_cmp_gt_i32_e64 s[62:63], 26, v173
	v_cmp_gt_i32_e64 s[64:65], 27, v173
	v_cmp_gt_i32_e64 s[60:61], 25, v173
	s_and_b64 s[62:63], s[64:65], s[62:63]
	v_cmp_gt_i32_e64 s[58:59], 24, v173
	s_and_b64 s[60:61], s[62:63], s[60:61]
	v_cmp_gt_i32_e64 s[56:57], 19, v173
	s_and_b64 s[58:59], s[60:61], s[58:59]
	v_cmp_gt_i32_e64 s[54:55], 18, v173
	s_and_b64 s[56:57], s[58:59], s[56:57]
	v_cmp_gt_i32_e64 s[52:53], 17, v173
	s_and_b64 s[54:55], s[56:57], s[54:55]
	v_cmp_gt_i32_e64 s[50:51], 16, v173
	s_and_b64 s[52:53], s[54:55], s[52:53]
	v_cmp_gt_i32_e64 s[48:49], 11, v173
	s_and_b64 s[50:51], s[52:53], s[50:51]
	v_cmp_gt_i32_e64 s[46:47], 10, v173
	s_and_b64 s[48:49], s[50:51], s[48:49]
	v_cmp_gt_i32_e64 s[44:45], 9, v173
	s_and_b64 s[46:47], s[48:49], s[46:47]
	v_cmp_gt_i32_e64 s[42:43], 8, v173
	s_and_b64 s[44:45], s[46:47], s[44:45]
	v_cmp_gt_i32_e64 s[40:41], 3, v173
	s_and_b64 s[42:43], s[44:45], s[42:43]
	v_cmp_gt_i32_e64 s[38:39], 2, v173
	s_and_b64 s[40:41], s[42:43], s[40:41]
	v_cmp_gt_i32_e64 s[36:37], 1, v173
	s_and_b64 s[38:39], s[40:41], s[38:39]
	v_cmp_gt_i32_e64 s[34:35], 0, v173
	s_and_b64 s[36:37], s[38:39], s[36:37]
	s_and_b64 s[34:35], s[36:37], s[34:35]
	v_cmp_gt_i32_e64 s[30:31], 58, v173
	v_cndmask_b32_e64 v64, v64, v164, s[34:35]
	v_cmp_gt_i32_e64 s[34:35], 59, v173
	v_cmp_gt_i32_e64 s[28:29], 57, v173
	s_and_b64 s[30:31], s[34:35], s[30:31]
	v_cmp_gt_i32_e64 s[26:27], 56, v173
	s_and_b64 s[28:29], s[30:31], s[28:29]
	v_cmp_gt_i32_e64 s[24:25], 51, v173
	s_and_b64 s[26:27], s[28:29], s[26:27]
	v_cmp_gt_i32_e64 s[22:23], 50, v173
	s_and_b64 s[24:25], s[26:27], s[24:25]
	v_cmp_gt_i32_e64 s[20:21], 49, v173
	s_and_b64 s[22:23], s[24:25], s[22:23]
	v_cmp_gt_i32_e64 s[18:19], 48, v173
	s_and_b64 s[20:21], s[22:23], s[20:21]
	v_cmp_gt_i32_e64 s[16:17], 43, v173
	s_and_b64 s[18:19], s[20:21], s[18:19]
	v_cmp_gt_i32_e64 s[14:15], 42, v173
	s_and_b64 s[16:17], s[18:19], s[16:17]
	v_cmp_gt_i32_e64 s[12:13], 41, v173
	s_and_b64 s[14:15], s[16:17], s[14:15]
	v_cmp_gt_i32_e64 s[10:11], 40, v173
	s_and_b64 s[12:13], s[14:15], s[12:13]
	v_cmp_gt_i32_e64 s[8:9], 35, v173
	s_and_b64 s[10:11], s[12:13], s[10:11]
	v_cmp_gt_i32_e64 s[6:7], 34, v173
	s_and_b64 s[8:9], s[10:11], s[8:9]
	v_cmp_gt_i32_e64 s[4:5], 33, v173
	s_and_b64 s[6:7], s[8:9], s[6:7]
	v_cmp_gt_i32_e32 vcc, 32, v173
	s_and_b64 s[4:5], s[6:7], s[4:5]
	s_and_b64 vcc, s[4:5], vcc
	v_cndmask_b32_e64 v79, v79, v164, s[64:65]
	v_cndmask_b32_e64 v78, v78, v164, s[62:63]
	v_cndmask_b32_e64 v77, v77, v164, s[60:61]
	v_cndmask_b32_e64 v76, v76, v164, s[58:59]
	v_cndmask_b32_e64 v75, v75, v164, s[56:57]
	v_cndmask_b32_e64 v74, v74, v164, s[54:55]
	v_cndmask_b32_e64 v73, v73, v164, s[52:53]
	v_cndmask_b32_e64 v72, v72, v164, s[50:51]
	v_cndmask_b32_e64 v71, v71, v164, s[48:49]
	v_cndmask_b32_e64 v70, v70, v164, s[46:47]
	v_cndmask_b32_e64 v69, v69, v164, s[44:45]
	v_cndmask_b32_e64 v68, v68, v164, s[42:43]
	v_cndmask_b32_e64 v67, v67, v164, s[40:41]
	v_cndmask_b32_e64 v66, v66, v164, s[38:39]
	v_cndmask_b32_e64 v65, v65, v164, s[36:37]
	v_cndmask_b32_e64 v63, v63, v164, s[34:35]
	v_cndmask_b32_e64 v62, v62, v164, s[30:31]
	v_cndmask_b32_e64 v61, v61, v164, s[28:29]
	v_cndmask_b32_e64 v60, v60, v164, s[26:27]
	v_cndmask_b32_e64 v59, v59, v164, s[24:25]
	v_cndmask_b32_e64 v58, v58, v164, s[22:23]
	v_cndmask_b32_e64 v57, v57, v164, s[20:21]
	v_cndmask_b32_e64 v56, v56, v164, s[18:19]
	v_cndmask_b32_e64 v55, v55, v164, s[16:17]
	v_cndmask_b32_e64 v54, v54, v164, s[14:15]
	v_cndmask_b32_e64 v53, v53, v164, s[12:13]
	v_cndmask_b32_e64 v52, v52, v164, s[10:11]
	v_cndmask_b32_e64 v51, v51, v164, s[8:9]
	v_cndmask_b32_e64 v50, v50, v164, s[6:7]
	v_cndmask_b32_e64 v49, v49, v164, s[4:5]
	v_cndmask_b32_e32 v48, v48, v164, vcc
	s_branch .LBB0_1417
.Lat_resc:
	s_and_saveexec_b64 s[4:5], s[2:3]
	ds_write_b32 v171, v128 offset:128
	s_or_b64 exec, exec, s[4:5]
	s_waitcnt lgkmcnt(0)
	ds_read_b128 v[132:135], v168 offset:224
	ds_read_b128 v[136:139], v168 offset:192
	ds_read_b128 v[140:143], v168 offset:160
	ds_read_b128 v[174:177], v168 offset:128
	s_waitcnt lgkmcnt(0)
	v_pk_mul_f32 v[30:31], v[30:31], v[134:135]
	v_pk_mul_f32 v[26:27], v[26:27], v[138:139]
	v_pk_mul_f32 v[22:23], v[22:23], v[142:143]
	v_pk_mul_f32 v[18:19], v[18:19], v[176:177]
	v_pk_mul_f32 v[28:29], v[28:29], v[132:133]
	v_pk_mul_f32 v[24:25], v[24:25], v[136:137]
	v_pk_mul_f32 v[20:21], v[20:21], v[140:141]
	v_pk_mul_f32 v[16:17], v[16:17], v[174:175]
	v_pk_mul_f32 v[14:15], v[14:15], v[134:135]
	v_pk_mul_f32 v[10:11], v[10:11], v[138:139]
	v_pk_mul_f32 v[6:7], v[6:7], v[142:143]
	v_pk_mul_f32 v[2:3], v[2:3], v[176:177]
	v_pk_mul_f32 v[12:13], v[12:13], v[132:133]
	v_pk_mul_f32 v[8:9], v[8:9], v[136:137]
	v_pk_mul_f32 v[4:5], v[4:5], v[140:141]
	v_pk_mul_f32 v[0:1], v[0:1], v[174:175]
	s_branch .LBB0_1422
